# phases 8 and 18: the workgroup in wave slot != 0 of a CU starts its first tile 10 us late so one workgroup streams GEMM operands while its CU partner runs the top-k sort
# speedup vs baseline: 1.0424x; 1.0045x over previous
.LBB0_491:
	s_getreg_b32 s98, hwreg(HW_REG_HW_ID, 0, 4)
	s_cmp_eq_u32 s98, 0
	s_cbranch_scc1 .Lstg0_done
	s_memrealtime s[98:99]
	s_waitcnt lgkmcnt(0)
	s_add_u32 s98, s98, 1000
.Lstg0_spin:
	s_sleep 8
	s_memrealtime s[100:101]
	s_waitcnt lgkmcnt(0)
	s_sub_u32 s101, s100, s98
	s_cmp_lt_i32 s101, 0
	s_cbranch_scc1 .Lstg0_spin
